# v20 + P3 token-tile loop: static s_setprio 1 for waves 4-7
# baseline (speedup 1.0000x reference)
; __device__ __forceinline__ unsigned pk2(float lo, float hi) { f32x2_t v = {lo, hi}; bf16x2_t b = __builtin_convertvector(v, bf16x2_t); return __builtin_bit_cast(unsigned, b); }
; __device__ __forceinline__ float sigmoidf_(float x) { return __builtin_amdgcn_rcpf(1.0f + __expf(-x)); }
; __device__ __forceinline__ f32x4 bf4(u32x2 w) { return (f32x4){__uint_as_float(w.x << 16), __uint_as_float(w.x & 0xffff0000u), __uint_as_float(w.y << 16), __uint_as_float(w.y & 0xffff0000u)}; }
; __device__ __forceinline__ void phase3(const P3Args& A, unsigned char* lds, int tid, int wave, int lane) {
;     ...
;         const size_t hb = ((size_t)(b * 8 + wave) * SEQ + s0) * 64;
;         const bf16* __restrict__ Rbr = A.Rb;
;         unsigned char* stg = lds + 67584 + wave * 7344;
;         u32x4 rowreg[7];
;     ...
;         { int zo0; asm volatile("v_mov_b32 %0, 0" : "=v"(zo0)); P3_ROWLOAD(0, lane + zo0); }
;     ...
;                 const unsigned char* rs = stg + fr * 144 + c4 * 2;
;                 const f32x4 r0 = bf4(*(const u32x2*)(rs)), r1 = bf4(*(const u32x2*)(rs + 144));
;                 const f32x4 k0 = bf4(*(const u32x2*)(rs + 17 * 144)), k1 = bf4(*(const u32x2*)(rs + 18 * 144));
;                 const f32x4 v0 = bf4(*(const u32x2*)(rs + 34 * 144)), v1 = bf4(*(const u32x2*)(rs + 35 * 144));
;                 const f32x4 rm = r1 + (r0 - r1) * mur, km = k1 + (k0 - k1) * muk, vm = v1 + (v0 - v1) * muv;
;                 f32x4 lw, ah;
; #pragma unroll
;                 for (int r = 0; r < 4; ++r) { lw[r] = -0.6065306597f * sigmoidf_(w0[r] + ad[r]); ah[r] = sigmoidf_(a0[r] + ai[r]); }
;                 const f32x4 kp = km * ((ah - 1.0f) * ka + 1.0f);
;                 const f32x4 pr3 = rm * kp * rk;
;                 float rks = (pr3[0] + pr3[1]) + (pr3[2] + pr3[3]);
;                 rks = rows4_sum(rks);
;                 if (fq == 0) RK[((size_t)t * 8 + wave) * 4 + ct] = rks;
;                 lwo[ct] = lw;
;                 ro[ct] = (u32x2){pk2(rm[0], rm[1]), pk2(rm[2], rm[3])}; ko[ct] = (u32x2){pk2(km[0], km[1]), pk2(km[2], km[3])};
;                 vo[ct] = (u32x2){pk2(vm[0], vm[1]), pk2(vm[2], vm[3])}; aho[ct] = (u32x2){pk2(ah[0], ah[1]), pk2(ah[2], ah[3])};
;                 go[ct] = (u32x2){pk2(ag[0], ag[1]), pk2(ag[2], ag[3])};
.LBB0_335:
	s_or_b64 exec, exec, s[0:1]
	s_ashr_i32 s0, s41, 31
	s_lshr_b32 s0, s0, 27
	s_add_i32 s0, s41, s0
	s_ashr_i32 s0, s0, 5
	s_lshl_b32 s0, s0, 3
	v_readlane_b32 s1, v242, 17
	s_add_i32 s0, s0, s1
	s_ashr_i32 s7, s6, 31
	s_ashr_i32 s1, s0, 31
	s_lshl_b64 s[4:5], s[0:1], 19
	s_lshl_b64 s[8:9], s[6:7], 7
	s_add_u32 s8, s4, s8
	s_addc_u32 s9, s5, s9
	s_lshl_b64 s[0:1], s[0:1], 20
	s_lshl_b64 s[4:5], s[6:7], 8
	s_add_u32 s10, s0, s4
	s_addc_u32 s11, s1, s5
	s_mov_b32 s12, 16
	v_mbcnt_lo_u32_b32 v211, -1, 0
	v_mbcnt_hi_u32_b32 v211, -1, v211
	v_readlane_b32 s98, v242, 17
	s_lshl_b32 s99, s98, 8
	v_lshl_add_u32 v212, v211, 2, s99
	v_readlane_b32 s100, v241, 38
	v_readlane_b32 s101, v241, 39
	s_nop 4
	global_load_dword v213, v212, s[100:101]
	v_readlane_b32 s100, v241, 32
	v_readlane_b32 s101, v241, 33
	s_nop 4
	global_load_dword v214, v212, s[100:101]
	global_load_dword v215, v212, s[100:101] offset:2048
	v_readlane_b32 s100, v242, 1
	v_readlane_b32 s101, v242, 2
	s_nop 4
	global_load_dword v216, v212, s[100:101]
	v_readlane_b32 s100, v241, 46
	v_readlane_b32 s101, v241, 47
	s_nop 4
	global_load_dword v217, v212, s[100:101]
	v_readlane_b32 s100, v241, 34
	v_readlane_b32 s101, v241, 35
	s_nop 4
	global_load_dword v218, v212, s[100:101]
	global_load_dword v219, v212, s[24:25]
	s_mul_i32 s99, s98, 1792
	s_add_i32 s99, s99, 126464
	v_lshl_add_u32 v220, v211, 2, s99
	s_waitcnt vmcnt(0)
	ds_write_b32 v220, v213
	ds_write_b32 v220, v214 offset:256
	ds_write_b32 v220, v215 offset:512
	ds_write_b32 v220, v216 offset:768
	ds_write_b32 v220, v217 offset:1024
	ds_write_b32 v220, v218 offset:1280
	ds_write_b32 v220, v219 offset:1536
	v_lshrrev_b32_e32 v210, 4, v211
	v_lshl_add_u32 v210, v210, 4, s99
	s_waitcnt lgkmcnt(0)
	v_lshlrev_b32_e32 v195, 3, v109
	v_add_u32_e32 v0, s58, v195
	v_ashrrev_i32_e32 v1, 31, v0
	v_lshlrev_b64 v[4:5], 1, v[0:1]
	v_lshl_add_u64 v[2:3], s[54:55], 0, v[4:5]
	global_load_dwordx4 v[212:215], v[2:3], off
	v_add_u32_e32 v2, s58, v0
	v_ashrrev_i32_e32 v3, 31, v2
	v_add_u32_e32 v0, 0x200, v0
	v_lshl_add_u64 v[6:7], v[2:3], 1, s[60:61]
	v_ashrrev_i32_e32 v1, 31, v0
	global_load_dwordx4 v[216:219], v[6:7], off
	v_lshlrev_b64 v[6:7], 1, v[0:1]
	v_lshl_add_u64 v[0:1], s[54:55], 0, v[6:7]
	v_lshl_add_u64 v[4:5], s[22:23], 0, v[4:5]
	global_load_dwordx4 v[220:223], v[0:1], off
	global_load_dwordx4 v[224:227], v[4:5], off
	v_add_u32_e32 v0, 0x200, v2
	v_ashrrev_i32_e32 v1, 31, v0
	v_lshl_add_u64 v[0:1], v[0:1], 1, s[60:61]
	global_load_dwordx4 v[228:231], v[0:1], off
	v_lshl_add_u64 v[4:5], s[22:23], 0, v[6:7]
	global_load_dwordx4 v[232:235], v[4:5], off
	v_add_u32_e32 v0, 0x400, v2
	v_ashrrev_i32_e32 v1, 31, v0
	v_lshl_add_u64 v[0:1], v[0:1], 1, s[60:61]
	global_load_dwordx4 v[236:239], v[0:1], off
	v_add_u32_e32 v0, 0x600, v2
	v_ashrrev_i32_e32 v1, 31, v0
	v_lshl_add_u64 v[0:1], v[0:1], 1, s[60:61]
	global_load_dwordx4 v[244:247], v[0:1], off
	s_waitcnt vmcnt(0)
	v_readlane_b32 s98, v242, 17
	s_cmp_lt_u32 s98, 4
	s_cbranch_scc1 .Lp3_noprio
	s_setprio 1
.Lp3_noprio:
	s_branch .LBB0_337
.LBB0_336:
	s_or_b64 exec, exec, s[0:1]
	s_waitcnt lgkmcnt(0)
	v_lshlrev_b32_e32 v110, 16, v104
	v_and_b32_e32 v118, 0xffff0000, v104
	v_lshlrev_b32_e32 v120, 16, v105
	v_and_b32_e32 v122, 0xffff0000, v105
	v_lshlrev_b32_e32 v104, 16, v106
	v_and_b32_e32 v105, 0xffff0000, v106
	v_sub_f32_e32 v119, v118, v105
	v_sub_f32_e32 v118, v110, v104
	s_waitcnt vmcnt(0)
	v_pk_fma_f32 v[100:101], v[100:101], v[118:119], v[104:105]
	v_cvt_pk_bf16_f32 v88, v88, v89
	v_cvt_pk_bf16_f32 v89, v90, v91
	v_lshlrev_b32_e32 v90, 16, v68
	v_and_b32_e32 v91, 0xffff0000, v68
	v_lshlrev_b32_e32 v110, 16, v69
	v_and_b32_e32 v118, 0xffff0000, v69
	v_lshlrev_b32_e32 v68, 16, v70
	v_and_b32_e32 v69, 0xffff0000, v70
	v_lshlrev_b32_e32 v70, 16, v71
	v_and_b32_e32 v71, 0xffff0000, v71
	v_sub_f32_e32 v91, v91, v69
	v_sub_f32_e32 v90, v90, v68
	v_sub_f32_e32 v119, v118, v71
	v_sub_f32_e32 v118, v110, v70
	v_pk_fma_f32 v[64:65], v[64:65], v[90:91], v[68:69]
	v_pk_fma_f32 v[118:119], v[66:67], v[118:119], v[70:71]
	v_cvt_pk_bf16_f32 v66, v64, v65
	v_add_f32_e32 v64, v80, v84
	v_mul_f32_e32 v64, 0xbfb8aa3b, v64
	v_exp_f32_e32 v68, v64
	v_add_f32_e32 v69, v82, v86
	v_mul_f32_e32 v69, 0xbfb8aa3b, v69
	v_exp_f32_e32 v69, v69
	v_add_f32_e32 v68, 1.0, v68
	v_rcp_f32_e32 v80, v68
	v_add_f32_e32 v68, v81, v85
	v_add_f32_e32 v81, v83, v87
	v_mul_f32_e32 v68, 0xbfb8aa3b, v68
	v_mul_f32_e32 v81, 0xbfb8aa3b, v81
	v_exp_f32_e32 v68, v68
	v_exp_f32_e32 v81, v81
	v_add_f32_e32 v69, 1.0, v69
	v_rcp_f32_e32 v82, v69
	v_add_f32_e32 v68, 1.0, v68
	v_add_f32_e32 v69, 1.0, v81
	v_rcp_f32_e32 v83, v69
	v_rcp_f32_e32 v81, v68
	v_cvt_pk_bf16_f32 v68, v56, v57
	v_cvt_pk_bf16_f32 v69, v58, v59
	v_pk_mul_f32 v[58:59], v[82:83], s[38:39] op_sel_hi:[1,0]
	v_pk_mul_f32 v[56:57], v[80:81], s[38:39] op_sel_hi:[1,0]
	v_lshlrev_b32_e32 v80, 16, v36
	v_and_b32_e32 v81, 0xffff0000, v36
	v_lshlrev_b32_e32 v82, 16, v37
	v_and_b32_e32 v83, 0xffff0000, v37
	v_lshlrev_b32_e32 v36, 16, v38
	v_and_b32_e32 v37, 0xffff0000, v38
	v_sub_f32_e32 v81, v81, v37
	v_sub_f32_e32 v80, v80, v36
	v_pk_fma_f32 v[32:33], v[32:33], v[80:81], v[36:37]
	v_add_f32_e32 v45, v53, v45
	v_cvt_pk_bf16_f32 v32, v32, v33
	v_add_f32_e32 v33, v52, v44
	v_add_f32_e32 v46, v54, v46
	v_add_f32_e32 v47, v55, v47
	v_mul_f32_e32 v33, 0xbfb8aa3b, v33
	v_mul_f32_e32 v45, 0xbfb8aa3b, v45
	v_mul_f32_e32 v46, 0xbfb8aa3b, v46
	v_mul_f32_e32 v47, 0xbfb8aa3b, v47
	v_exp_f32_e32 v44, v33
	v_exp_f32_e32 v45, v45
	v_exp_f32_e32 v46, v46
	v_exp_f32_e32 v47, v47
	v_add_f32_e32 v44, 1.0, v44
	v_add_f32_e32 v45, 1.0, v45
	v_add_f32_e32 v46, 1.0, v46
	v_add_f32_e32 v47, 1.0, v47
; __device__ __forceinline__ unsigned pk2(float lo, float hi) { f32x2_t v = {lo, hi}; bf16x2_t b = __builtin_convertvector(v, bf16x2_t); return __builtin_bit_cast(unsigned, b); }
; __device__ __forceinline__ float sigmoidf_(float x) { return __builtin_amdgcn_rcpf(1.0f + __expf(-x)); }
; #define LDS_WAIT() asm volatile("s_waitcnt lgkmcnt(0)" ::: "memory")
; __device__ __forceinline__ void phase3(const P3Args& A, unsigned char* lds, int tid, int wave, int lane) {
;     ...
;                 for (int r = 0; r < 4; ++r) { lw[r] = -0.6065306597f * sigmoidf_(w0[r] + ad[r]); ah[r] = sigmoidf_(a0[r] + ai[r]); }
;                 const f32x4 kp = km * ((ah - 1.0f) * ka + 1.0f);
;                 const f32x4 pr3 = rm * kp * rk;
;                 float rks = (pr3[0] + pr3[1]) + (pr3[2] + pr3[3]);
;                 rks = rows4_sum(rks);
;                 if (fq == 0) RK[((size_t)t * 8 + wave) * 4 + ct] = rks;
;                 lwo[ct] = lw;
;                 ro[ct] = (u32x2){pk2(rm[0], rm[1]), pk2(rm[2], rm[3])}; ko[ct] = (u32x2){pk2(km[0], km[1]), pk2(km[2], km[3])};
;                 vo[ct] = (u32x2){pk2(vm[0], vm[1]), pk2(vm[2], vm[3])}; aho[ct] = (u32x2){pk2(ah[0], ah[1]), pk2(ah[2], ah[3])};
;                 go[ct] = (u32x2){pk2(ag[0], ag[1]), pk2(ag[2], ag[3])};
;                 asm volatile("" ::: "memory");
;             }
;             P3_ROWLOAD((tt < 7) ? tt + 1 : 7, ln);
;             LDS_WAIT();
;             const size_t ob = hb + (size_t)(tt * 16) * 64;
;     ...
;             P3_STAGE_BF16(Rr, ro); P3_STAGE_BF16(Kr, ko); P3_STAGE_BF16(Vr, vo); P3_STAGE_BF16(AH, aho); P3_STAGE_BF16(G, go);
	v_rcp_f32_e32 v44, v44
	v_rcp_f32_e32 v46, v46
	v_rcp_f32_e32 v47, v47
	v_rcp_f32_e32 v45, v45
	v_cvt_pk_bf16_f32 v55, v10, v11
	v_add_f32_e32 v11, v27, v23
	v_add_f32_e32 v0, v4, v0
	v_cvt_pk_bf16_f32 v52, v28, v29
	v_cvt_pk_bf16_f32 v53, v30, v31
	v_pk_mul_f32 v[30:31], v[46:47], s[38:39] op_sel_hi:[1,0]
	v_pk_mul_f32 v[28:29], v[44:45], s[38:39] op_sel_hi:[1,0]
	v_lshlrev_b32_e32 v44, 16, v16
	v_and_b32_e32 v45, 0xffff0000, v16
	v_lshlrev_b32_e32 v46, 16, v17
	v_and_b32_e32 v47, 0xffff0000, v17
	v_lshlrev_b32_e32 v16, 16, v18
	v_and_b32_e32 v17, 0xffff0000, v18
	v_mul_f32_e32 v11, 0xbfb8aa3b, v11
	v_mul_f32_e32 v0, 0xbfb8aa3b, v0
	v_sub_f32_e32 v45, v45, v17
	v_sub_f32_e32 v44, v44, v16
	v_exp_f32_e32 v11, v11
	v_exp_f32_e32 v0, v0
	v_pk_fma_f32 v[12:13], v[12:13], v[44:45], v[16:17]
	v_cvt_pk_bf16_f32 v54, v8, v9
	v_cvt_pk_bf16_f32 v44, v12, v13
	v_add_f32_e32 v12, v24, v20
	v_add_f32_e32 v9, v25, v21
	v_mul_f32_e32 v12, 0xbfb8aa3b, v12
	v_mul_f32_e32 v9, 0xbfb8aa3b, v9
	v_exp_f32_e32 v12, v12
	v_exp_f32_e32 v9, v9
	v_add_f32_e32 v4, 1.0, v11
	v_add_f32_e32 v0, 1.0, v0
	v_rcp_f32_e32 v11, v4
	v_rcp_f32_e32 v4, v0
	v_add_f32_e32 v0, v5, v1
	v_add_f32_e32 v1, v6, v2
	v_mul_f32_e32 v1, 0xbfb8aa3b, v1
	v_add_f32_e32 v2, v7, v3
	v_add_f32_e32 v10, v26, v22
	v_mul_f32_e32 v0, 0xbfb8aa3b, v0
	v_exp_f32_e32 v1, v1
	v_mul_f32_e32 v2, 0xbfb8aa3b, v2
	v_add_f32_e32 v8, 1.0, v12
	v_mul_f32_e32 v10, 0xbfb8aa3b, v10
	v_add_f32_e32 v9, 1.0, v9
	v_exp_f32_e32 v0, v0
	v_exp_f32_e32 v2, v2
	v_exp_f32_e32 v10, v10
	v_rcp_f32_e32 v8, v8
	v_rcp_f32_e32 v9, v9
	v_add_f32_e32 v1, 1.0, v1
	v_add_f32_e32 v0, 1.0, v0
	v_rcp_f32_e32 v6, v1
	v_add_f32_e32 v1, 1.0, v2
	v_add_f32_e32 v10, 1.0, v10
	v_rcp_f32_e32 v7, v1
	v_rcp_f32_e32 v5, v0
	v_pk_mul_f32 v[0:1], v[8:9], s[38:39] op_sel_hi:[1,0]
	v_ashrrev_i32_e32 v8, 3, v116
	v_lshlrev_b32_e32 v106, 16, v107
	v_and_b32_e32 v107, 0xffff0000, v107
	v_rcp_f32_e32 v10, v10
	v_mul_lo_u32 v9, v8, s3
	v_sub_f32_e32 v155, v122, v107
	v_sub_f32_e32 v154, v120, v106
	v_cvt_pk_bf16_f32 v36, v148, v149
	v_cvt_pk_bf16_f32 v37, v146, v147
	v_lshlrev_b32_e32 v18, 16, v19
	v_and_b32_e32 v19, 0xffff0000, v19
	v_cvt_pk_bf16_f32 v16, v134, v135
	v_cvt_pk_bf16_f32 v17, v136, v137
	v_add3_u32 v22, s39, v129, v9
	v_ashrrev_i32_e32 v9, 31, v8
	v_pk_fma_f32 v[154:155], v[102:103], v[154:155], v[106:107]
	v_cvt_pk_bf16_f32 v106, v174, v175
	v_cvt_pk_bf16_f32 v107, v172, v173
	v_cvt_pk_bf16_f32 v90, v162, v163
	v_cvt_pk_bf16_f32 v91, v160, v161
	v_sub_f32_e32 v47, v47, v19
	v_sub_f32_e32 v46, v46, v18
	s_waitcnt lgkmcnt(0)
	ds_write2_b64 v182, v[16:17], v[36:37] offset1:4
	ds_write2_b64 v182, v[90:91], v[106:107] offset0:8 offset1:12
	v_lshlrev_b64 v[8:9], 7, v[8:9]
	s_add_u32 s0, s28, s8
	v_pk_fma_f32 v[14:15], v[14:15], v[46:47], v[18:19]
	s_waitcnt lgkmcnt(0)
	v_or_b32_e32 v8, v8, v129
	s_addc_u32 s1, s29, s9
	v_cvt_pk_bf16_f32 v45, v14, v15
	v_pk_mul_f32 v[2:3], v[10:11], s[38:39] op_sel_hi:[1,0]
	v_lshl_add_u64 v[16:17], s[0:1], 0, v[8:9]
	ds_read_b128 v[8:11], v22
	ds_read_b128 v[12:15], v22 offset:1152
	s_mov_b32 s0, 0x11800000
	v_lshlrev_b32_e32 v38, 16, v39
	v_and_b32_e32 v39, 0xffff0000, v39
	v_add_co_u32_e64 v20, s[0:1], s0, v16
	v_sub_f32_e32 v83, v83, v39
	v_sub_f32_e32 v82, v82, v38
	v_addc_co_u32_e64 v21, s[0:1], 0, v17, s[0:1]
	v_pk_fma_f32 v[34:35], v[34:35], v[82:83], v[38:39]
	v_cvt_pk_bf16_f32 v38, v152, v153
	v_cvt_pk_bf16_f32 v39, v150, v151
	v_cvt_pk_bf16_f32 v18, v138, v139
	v_cvt_pk_bf16_f32 v19, v140, v141
	s_waitcnt lgkmcnt(1)
	global_store_dwordx4 v[20:21], v[8:11], off
	s_waitcnt lgkmcnt(0)
	global_store_dwordx4 v[20:21], v[12:15], off offset:1024
	v_cvt_pk_bf16_f32 v104, v178, v179
	v_cvt_pk_bf16_f32 v105, v176, v177
	v_cvt_pk_bf16_f32 v70, v166, v167
	v_cvt_pk_bf16_f32 v71, v164, v165
	s_waitcnt lgkmcnt(0)
; #define LDS_WAIT() asm volatile("s_waitcnt lgkmcnt(0)" ::: "memory")
; __device__ __forceinline__ void phase3(const P3Args& A, unsigned char* lds, int tid, int wave, int lane) {
;     ...
;             P3_STAGE_BF16(Rr, ro); P3_STAGE_BF16(Kr, ko); P3_STAGE_BF16(Vr, vo); P3_STAGE_BF16(AH, aho); P3_STAGE_BF16(G, go);
;     ...
;             {
; #pragma unroll
;                 for (int ct = 0; ct < 4; ++ct) *(f32x4*)(stg + fr * 272 + (ct * 16 + fq * 4) * 4) = lwo[ct];
;                 LDS_WAIT();
; #pragma unroll
;                 for (int j = 0; j < 4; ++j) { const int tk = (ln >> 4) + 4 * j, c4 = (ln & 15) * 4;
;                     const f32x4 v = *(const f32x4*)(stg + tk * 272 + c4 * 4); *(f32x4*)(LW + ob + (size_t)tk * 64 + c4) = v; }
;                 LDS_WAIT();
;             }
;         }
	ds_write2_b64 v182, v[18:19], v[38:39] offset1:4
	ds_write2_b64 v182, v[70:71], v[104:105] offset0:8 offset1:12
	s_waitcnt lgkmcnt(0)
	ds_read_b128 v[8:11], v22
	ds_read_b128 v[12:15], v22 offset:1152
	s_mov_b32 s0, 0x13800000
	v_add_co_u32_e64 v18, s[0:1], s0, v16
	v_cvt_pk_bf16_f32 v33, v34, v35
	s_nop 0
	v_addc_co_u32_e64 v19, s[0:1], 0, v17, s[0:1]
	s_waitcnt lgkmcnt(1)
	global_store_dwordx4 v[18:19], v[8:11], off
	s_waitcnt lgkmcnt(0)
	global_store_dwordx4 v[18:19], v[12:15], off offset:1024
	v_cvt_pk_bf16_f32 v102, v100, v101
	v_cvt_pk_bf16_f32 v103, v154, v155
	v_cvt_pk_bf16_f32 v67, v118, v119
	s_waitcnt lgkmcnt(0)
	ds_write2_b64 v182, v[44:45], v[32:33] offset1:4
	ds_write2_b64 v182, v[66:67], v[102:103] offset0:8 offset1:12
	s_waitcnt lgkmcnt(0)
	ds_read_b128 v[8:11], v22
	ds_read_b128 v[12:15], v22 offset:1152
	s_mov_b32 s0, 0x15800000
	v_add_co_u32_e64 v18, s[0:1], s0, v16
	v_cvt_pk_bf16_f32 v34, v142, v143
	s_nop 0
	v_addc_co_u32_e64 v19, s[0:1], 0, v17, s[0:1]
	v_cvt_pk_bf16_f32 v35, v144, v145
	v_cvt_pk_bf16_f32 v46, v130, v131
	v_cvt_pk_bf16_f32 v47, v132, v133
	s_waitcnt lgkmcnt(1)
	global_store_dwordx4 v[18:19], v[8:11], off
	s_waitcnt lgkmcnt(0)
	global_store_dwordx4 v[18:19], v[12:15], off offset:1024
	v_cvt_pk_bf16_f32 v100, v168, v169
	v_cvt_pk_bf16_f32 v101, v170, v171
	v_cvt_pk_bf16_f32 v64, v156, v157
	v_cvt_pk_bf16_f32 v65, v158, v159
	s_waitcnt lgkmcnt(0)
	ds_write2_b64 v182, v[46:47], v[34:35] offset1:4
	ds_write2_b64 v182, v[64:65], v[100:101] offset0:8 offset1:12
	s_waitcnt lgkmcnt(0)
	ds_read_b128 v[8:11], v22
	ds_read_b128 v[12:15], v22 offset:1152
	s_mov_b32 s0, 0x4800000
	v_add_co_u32_e64 v18, s[0:1], s0, v16
	v_pk_mul_f32 v[6:7], v[6:7], s[38:39] op_sel_hi:[1,0]
	s_nop 0
	v_addc_co_u32_e64 v19, s[0:1], 0, v17, s[0:1]
	s_waitcnt lgkmcnt(1)
	global_store_dwordx4 v[18:19], v[8:11], off
	s_waitcnt lgkmcnt(0)
	global_store_dwordx4 v[18:19], v[12:15], off offset:1024
	s_waitcnt lgkmcnt(0)
	ds_write2_b64 v182, v[54:55], v[52:53] offset1:4
	ds_write2_b64 v182, v[68:69], v[88:89] offset0:8 offset1:12
	s_waitcnt lgkmcnt(0)
	ds_read_b128 v[8:11], v22
	ds_read_b128 v[12:15], v22 offset:1152
	s_mov_b32 s0, 0x2800000
	v_add_co_u32_e64 v16, s[0:1], s0, v16
	v_pk_mul_f32 v[4:5], v[4:5], s[38:39] op_sel_hi:[1,0]
	s_nop 0
	v_addc_co_u32_e64 v17, s[0:1], 0, v17, s[0:1]
	s_waitcnt lgkmcnt(1)
	global_store_dwordx4 v[16:17], v[8:11], off
	s_waitcnt lgkmcnt(0)
	global_store_dwordx4 v[16:17], v[12:15], off offset:1024
	s_waitcnt lgkmcnt(0)
	s_add_u32 s0, s28, s10
	v_mul_lo_u32 v8, v180, s2
	v_add3_u32 v8, s39, v8, v181
	ds_write_b128 v8, v[4:7]
	ds_write_b128 v8, v[0:3] offset:64
	ds_write_b128 v8, v[28:31] offset:128
	ds_write_b128 v8, v[56:59] offset:192
	v_ashrrev_i32_e32 v0, 4, v116
	v_and_b32_e32 v1, 0xf0, v127
	v_mul_lo_u32 v2, v0, s2
	v_add3_u32 v12, s39, v1, v2
	v_ashrrev_i32_e32 v1, 31, v0
	v_lshlrev_b64 v[0:1], 8, v[0:1]
	v_and_b32_e32 v2, 15, v116
	s_waitcnt lgkmcnt(0)
	v_lshl_or_b32 v0, v2, 4, v0
	s_addc_u32 s1, s29, s11
	v_lshl_add_u64 v[16:17], s[0:1], 0, v[0:1]
	ds_read_b128 v[0:3], v12
	ds_read_b128 v[4:7], v12 offset:1088
	ds_read_b128 v[8:11], v12 offset:2176
	ds_read_b128 v[12:15], v12 offset:3264
	s_mov_b32 s0, 0x17800000
	v_add_co_u32_e64 v16, s[0:1], s0, v16
	s_add_i32 s12, s12, 16
	s_nop 0
	v_addc_co_u32_e64 v17, s[0:1], 0, v17, s[0:1]
	s_add_u32 s8, s8, 0x800
	s_waitcnt lgkmcnt(3)
	global_store_dwordx4 v[16:17], v[0:3], off
	s_waitcnt lgkmcnt(2)
	global_store_dwordx4 v[16:17], v[4:7], off offset:1024
	s_waitcnt lgkmcnt(1)
	global_store_dwordx4 v[16:17], v[8:11], off offset:2048
	s_waitcnt lgkmcnt(0)
	global_store_dwordx4 v[16:17], v[12:15], off offset:3072
	s_addc_u32 s9, s9, 0
	s_add_u32 s10, s10, 0x1000
	s_waitcnt lgkmcnt(0)
	s_addc_u32 s11, s11, 0
	s_cmpk_eq_i32 s12, 0x90
	s_cbranch_scc1 .LBB0_310

; __device__ __forceinline__ void xcd_barrier(const XcdBarrier& b) {
;     asm volatile("s_waitcnt vmcnt(0)" ::: "memory");
;     __syncthreads();
;     if (threadIdx.x == 0) {
;         unsigned* bar = b.bar;
;         __builtin_amdgcn_s_waitcnt(0);
;         unsigned nloc = b.st[0], nx = b.st[1];
;         if (nloc == 0u) { xcd_barrier_complete(bar, b.x, nloc, nx); b.st[0] = nloc; b.st[1] = nx; }
.LBB0_374:
	s_setprio 0
	s_waitcnt vmcnt(0)
	s_barrier
	s_and_saveexec_b64 s[0:1], s[92:93]
	s_cbranch_execz .LBB0_426
	s_add_i32 s2, 0, 0x23ff0
	v_mov_b32_e32 v0, s2
	s_waitcnt vmcnt(0) expcnt(0) lgkmcnt(0)
	ds_read_b32 v2, v0
	s_add_i32 s2, 0, 0x23ff4
	v_mov_b32_e32 v0, s2
	ds_read_b32 v0, v0
	s_waitcnt lgkmcnt(1)
	v_cmp_ne_u32_e32 vcc, 0, v2
	s_cbranch_vccnz .LBB0_390
	s_mov_b32 s2, 1
	v_mov_b32_e32 v16, 0
	s_branch .LBB0_378
